# plus: 71% of compressed-KV page conversions moved from P0 into P1 tail slack (WG>=73)
# speedup vs baseline: 1.0183x; 1.0073x over previous
.LBB0_7:
	s_nop 0
	v_readlane_b32 s0, v254, 2
	v_readlane_b32 s1, v254, 3
	v_writelane_b32 v254, s48, 40
	s_cmp_lt_i32 s0, 1
	s_cselect_b64 s[4:5], -1, 0
	v_writelane_b32 v254, s49, 41
	v_writelane_b32 v254, s50, 42
	s_cmp_gt_i32 s1, 0
	v_writelane_b32 v254, s51, 43
	s_cselect_b64 s[6:7], -1, 0
	v_writelane_b32 v254, s52, 44
	s_and_b64 s[6:7], s[4:5], s[6:7]
	v_writelane_b32 v254, s53, 45
	s_andn2_b64 vcc, exec, s[6:7]
	v_and_b32_e32 v206, 63, v0
	v_writelane_b32 v254, s54, 46
	v_writelane_b32 v254, s55, 47
	s_cbranch_vccnz .LBB0_113
	s_movk_i32 s98, 0x2a7f
	v_readlane_b32 s0, v254, 0
	v_readlane_b32 s1, v254, 1
	s_load_dword s8, s[0:1], 0xe8
	v_readfirstlane_b32 s0, v0
	s_lshr_b32 s9, s0, 6
	s_lshl_b32 s0, s2, 3
	s_add_i32 s10, s9, s0
	s_waitcnt lgkmcnt(0)
	s_cmp_le_u32 s8, 73
	s_cbranch_scc1 .Lrc_nb
	s_sub_u32 s0, s8, 73
	s_lshl_b32 s0, s0, 3
	s_sub_u32 s98, s98, s0
.Lrc_nb:
	s_lshl_b32 s3, s8, 3
	s_cmpk_gt_i32 s10, 0x267f
	v_and_b32_e32 v34, 63, v0
	s_cbranch_scc1 .LBB0_78
	s_mov_b64 exec, -1
	v_readlane_b32 s0, v254, 0
	v_readlane_b32 s1, v254, 1
	s_nop 4
	s_load_dwordx2 s[56:57], s[0:1], 0x50
	s_load_dwordx2 s[58:59], s[0:1], 0x98
	s_load_dwordx2 s[60:61], s[0:1], 0x60
	s_load_dwordx2 s[62:63], s[0:1], 0xd8
	s_load_dwordx2 s[64:65], s[0:1], 0x48
	v_readfirstlane_b32 s4, v0
	v_and_b32_e32 v7, 63, v0
	s_lshr_b32 s4, s4, 6
	v_lshrrev_b32_e32 v1, 3, v7
	v_and_b32_e32 v2, 7, v7
	s_lshl_b32 s5, s4, 14
	v_lshlrev_b32_e32 v5, 5, v2
	s_movk_i32 s18, 0x420
	v_mul_u32_u24_e32 v4, s18, v2
	v_lshlrev_b32_e32 v2, 4, v2
	s_movk_i32 s18, 0x84
	v_mad_u32_u24 v3, v1, s18, v2
	v_lshl_add_u32 v4, v1, 2, v4
	v_add_u32_e32 v3, s5, v3
	v_add_u32_e32 v4, s5, v4
	v_mov_b32_e32 v148, v3
	v_add_u32_e32 v149, 1056, v3
	v_add_u32_e32 v150, 2112, v3
	v_add_u32_e32 v151, 3168, v3
	v_add_u32_e32 v152, 4224, v3
	v_add_u32_e32 v153, 5280, v3
	v_add_u32_e32 v154, 6336, v3
	v_add_u32_e32 v155, 7392, v3
	s_waitcnt lgkmcnt(0)
	s_mov_b32 s20, s10
	s_mov_b32 s21, s3
	s_cmp_ge_u32 s20, 0x2680
	s_cbranch_scc1 .LBB0_78
	s_mov_b32 s26, s20
	s_cmp_lt_u32 s26, 0x2080
	s_cbranch_scc1 .Ltrp0_i1_s0
	s_sub_u32 s26, s26, 0x2080
	s_cmp_lt_u32 s26, 0x400
	s_cbranch_scc1 .Ltrp0_i1_s1
	s_sub_u32 s26, s26, 0x400
	s_cmp_lt_u32 s26, 0x100
	s_cbranch_scc1 .Ltrp0_i1_s2
	s_sub_u32 s26, s26, 0x100
	s_branch .Ltrp0_i1_s3

.LBB0_325:
	s_cmp_eq_u32 s99, 5
	s_cbranch_scc0 .Lrc_p1skip
	s_cmp_lt_u32 s100, 73
	s_cbranch_scc1 .Lrc_p1skip
	s_mov_b32 s99, 7
	s_mov_b64 exec, -1
	v_readlane_b32 s0, v254, 0
	v_readlane_b32 s1, v254, 1
	v_readlane_b32 s52, v254, 44
	v_readlane_b32 s53, v254, 45
	v_readlane_b32 s54, v254, 46
	v_readlane_b32 s55, v254, 47
	s_nop 4
	s_load_dwordx16 s[76:91], s[0:1], 0x0
	s_load_dword s8, s[0:1], 0xe8
	s_waitcnt lgkmcnt(0)
	s_add_u32 s2, s100, 0x550
	s_sub_u32 s2, s2, s8
	s_sub_u32 s8, s8, 73
	s_movk_i32 s98, 0x2a7f
	v_readfirstlane_b32 s9, v0
	s_lshr_b32 s9, s9, 6
	s_lshl_b32 s10, s2, 3
	s_add_u32 s10, s10, s9
	s_lshl_b32 s3, s8, 3
	v_and_b32_e32 v34, 63, v0
	s_branch .LBB0_78
